# modp_task beside the chain: 8 weight-row loads in flight per iteration instead of hipcc's one-at-a-time; plus pooling rows moved beside the chain
# speedup vs baseline: 1.0018x; 1.0018x over previous
; __device__ __forceinline__ void modp_task(const Params& p, int l, int task, LAS float* sl) {
;     ...
;     const float* wp = p.w_ada + ((size_t)l * D + k0) * 12288 + n0;
; #pragma unroll 8
;     for (int kk = 0; kk < 64; ++kk) { const f32x4 w = __builtin_nontemporal_load((const f32x4*)(wp + (size_t)kk * 12288));
; #pragma unroll
;         for (int r = 0; r < 5; ++r) acc[r] += sl[r * 64 + kk] * w; }
.LBB0_534:
	v_lshl_add_u64 v[36:37], v[22:23], 0, s[2:3]
	v_mov_b32_e32 v54, s19
	s_mov_b32 s21, 0
	s_mov_b32 s20, 0x6000000
	v_lshl_add_u64 v[130:131], v[36:37], 0, s[20:21]
	s_mov_b32 s20, 0x600c000
	v_lshl_add_u64 v[132:133], v[36:37], 0, s[20:21]
	s_mov_b32 s20, 0x6018000
	v_lshl_add_u64 v[134:135], v[36:37], 0, s[20:21]
	s_mov_b32 s20, 0x6024000
	v_lshl_add_u64 v[136:137], v[36:37], 0, s[20:21]
	s_mov_b32 s20, 0x6030000
	v_lshl_add_u64 v[138:139], v[36:37], 0, s[20:21]
	s_mov_b32 s20, 0x603c000
	v_lshl_add_u64 v[140:141], v[36:37], 0, s[20:21]
	s_mov_b32 s20, 0x6048000
	v_lshl_add_u64 v[142:143], v[36:37], 0, s[20:21]
	s_mov_b32 s20, 0x6054000
	v_lshl_add_u64 v[144:145], v[36:37], 0, s[20:21]
	global_load_dwordx4 v[170:173], v[130:131], off nt
	global_load_dwordx4 v[174:177], v[132:133], off nt
	global_load_dwordx4 v[178:181], v[134:135], off nt
	global_load_dwordx4 v[182:185], v[136:137], off nt
	global_load_dwordx4 v[186:189], v[138:139], off nt
	global_load_dwordx4 v[190:193], v[140:141], off nt
	global_load_dwordx4 v[204:207], v[142:143], off nt
	global_load_dwordx4 v[208:211], v[144:145], off nt
	ds_read_b128 v[28:31], v54
	ds_read_b128 v[32:35], v54 offset:16
	ds_read_b128 v[38:41], v54 offset:256
	ds_read_b128 v[42:45], v54 offset:272
	ds_read_b128 v[46:49], v54 offset:512
	ds_read_b128 v[50:53], v54 offset:528
	ds_read_b128 v[212:215], v54 offset:768
	ds_read_b128 v[216:219], v54 offset:784
	ds_read_b128 v[220:223], v54 offset:1024
	ds_read_b128 v[224:227], v54 offset:1040
	s_add_u32 s2, s2, 0x60000
	s_addc_u32 s3, s3, 0
	s_add_i32 s19, s19, 32
	s_waitcnt lgkmcnt(0)
	s_waitcnt vmcnt(7)
	v_fmac_f32_e32 v16, v28, v170
	v_fmac_f32_e32 v17, v28, v171
	v_fmac_f32_e32 v18, v28, v172
	v_fmac_f32_e32 v19, v28, v173
	v_fmac_f32_e32 v12, v38, v170
	v_fmac_f32_e32 v13, v38, v171
	v_fmac_f32_e32 v14, v38, v172
	v_fmac_f32_e32 v15, v38, v173
	v_fmac_f32_e32 v8, v46, v170
	v_fmac_f32_e32 v9, v46, v171
	v_fmac_f32_e32 v10, v46, v172
	v_fmac_f32_e32 v11, v46, v173
	v_fmac_f32_e32 v4, v212, v170
	v_fmac_f32_e32 v5, v212, v171
	v_fmac_f32_e32 v6, v212, v172
	v_fmac_f32_e32 v7, v212, v173
	v_fmac_f32_e32 v0, v220, v170
	v_fmac_f32_e32 v1, v220, v171
	v_fmac_f32_e32 v2, v220, v172
	v_fmac_f32_e32 v3, v220, v173
	s_waitcnt vmcnt(6)
	v_fmac_f32_e32 v16, v29, v174
	v_fmac_f32_e32 v17, v29, v175
	v_fmac_f32_e32 v18, v29, v176
	v_fmac_f32_e32 v19, v29, v177
	v_fmac_f32_e32 v12, v39, v174
	v_fmac_f32_e32 v13, v39, v175
	v_fmac_f32_e32 v14, v39, v176
	v_fmac_f32_e32 v15, v39, v177
	v_fmac_f32_e32 v8, v47, v174
	v_fmac_f32_e32 v9, v47, v175
	v_fmac_f32_e32 v10, v47, v176
	v_fmac_f32_e32 v11, v47, v177
	v_fmac_f32_e32 v4, v213, v174
	v_fmac_f32_e32 v5, v213, v175
	v_fmac_f32_e32 v6, v213, v176
	v_fmac_f32_e32 v7, v213, v177
	v_fmac_f32_e32 v0, v221, v174
	v_fmac_f32_e32 v1, v221, v175
	v_fmac_f32_e32 v2, v221, v176
	v_fmac_f32_e32 v3, v221, v177
	s_waitcnt vmcnt(5)
	v_fmac_f32_e32 v16, v30, v178
	v_fmac_f32_e32 v17, v30, v179
	v_fmac_f32_e32 v18, v30, v180
	v_fmac_f32_e32 v19, v30, v181
	v_fmac_f32_e32 v12, v40, v178
	v_fmac_f32_e32 v13, v40, v179
	v_fmac_f32_e32 v14, v40, v180
	v_fmac_f32_e32 v15, v40, v181
	v_fmac_f32_e32 v8, v48, v178
	v_fmac_f32_e32 v9, v48, v179
	v_fmac_f32_e32 v10, v48, v180
	v_fmac_f32_e32 v11, v48, v181
	v_fmac_f32_e32 v4, v214, v178
	v_fmac_f32_e32 v5, v214, v179
	v_fmac_f32_e32 v6, v214, v180
	v_fmac_f32_e32 v7, v214, v181
	v_fmac_f32_e32 v0, v222, v178
	v_fmac_f32_e32 v1, v222, v179
	v_fmac_f32_e32 v2, v222, v180
	v_fmac_f32_e32 v3, v222, v181
	s_waitcnt vmcnt(4)
	v_fmac_f32_e32 v16, v31, v182
	v_fmac_f32_e32 v17, v31, v183
	v_fmac_f32_e32 v18, v31, v184
	v_fmac_f32_e32 v19, v31, v185
	v_fmac_f32_e32 v12, v41, v182
	v_fmac_f32_e32 v13, v41, v183
	v_fmac_f32_e32 v14, v41, v184
	v_fmac_f32_e32 v15, v41, v185
	v_fmac_f32_e32 v8, v49, v182
	v_fmac_f32_e32 v9, v49, v183
	v_fmac_f32_e32 v10, v49, v184
	v_fmac_f32_e32 v11, v49, v185
	v_fmac_f32_e32 v4, v215, v182
	v_fmac_f32_e32 v5, v215, v183
	v_fmac_f32_e32 v6, v215, v184
	v_fmac_f32_e32 v7, v215, v185
	v_fmac_f32_e32 v0, v223, v182
	v_fmac_f32_e32 v1, v223, v183
	v_fmac_f32_e32 v2, v223, v184
	v_fmac_f32_e32 v3, v223, v185
	s_waitcnt vmcnt(3)
	v_fmac_f32_e32 v16, v32, v186
	v_fmac_f32_e32 v17, v32, v187
	v_fmac_f32_e32 v18, v32, v188
	v_fmac_f32_e32 v19, v32, v189
	v_fmac_f32_e32 v12, v42, v186
	v_fmac_f32_e32 v13, v42, v187
	v_fmac_f32_e32 v14, v42, v188
	v_fmac_f32_e32 v15, v42, v189
	v_fmac_f32_e32 v8, v50, v186
	v_fmac_f32_e32 v9, v50, v187
	v_fmac_f32_e32 v10, v50, v188
	v_fmac_f32_e32 v11, v50, v189
	v_fmac_f32_e32 v4, v216, v186
	v_fmac_f32_e32 v5, v216, v187
	v_fmac_f32_e32 v6, v216, v188
	v_fmac_f32_e32 v7, v216, v189
	v_fmac_f32_e32 v0, v224, v186
	v_fmac_f32_e32 v1, v224, v187
	v_fmac_f32_e32 v2, v224, v188
	v_fmac_f32_e32 v3, v224, v189
	s_waitcnt vmcnt(2)
	v_fmac_f32_e32 v16, v33, v190
	v_fmac_f32_e32 v17, v33, v191
	v_fmac_f32_e32 v18, v33, v192
	v_fmac_f32_e32 v19, v33, v193
	v_fmac_f32_e32 v12, v43, v190
	v_fmac_f32_e32 v13, v43, v191
	v_fmac_f32_e32 v14, v43, v192
	v_fmac_f32_e32 v15, v43, v193
	v_fmac_f32_e32 v8, v51, v190
	v_fmac_f32_e32 v9, v51, v191
	v_fmac_f32_e32 v10, v51, v192
	v_fmac_f32_e32 v11, v51, v193
	v_fmac_f32_e32 v4, v217, v190
	v_fmac_f32_e32 v5, v217, v191
	v_fmac_f32_e32 v6, v217, v192
	v_fmac_f32_e32 v7, v217, v193
	v_fmac_f32_e32 v0, v225, v190
	v_fmac_f32_e32 v1, v225, v191
	v_fmac_f32_e32 v2, v225, v192
	v_fmac_f32_e32 v3, v225, v193
	s_waitcnt vmcnt(1)
	v_fmac_f32_e32 v16, v34, v204
	v_fmac_f32_e32 v17, v34, v205
	v_fmac_f32_e32 v18, v34, v206
	v_fmac_f32_e32 v19, v34, v207
	v_fmac_f32_e32 v12, v44, v204
	v_fmac_f32_e32 v13, v44, v205
	v_fmac_f32_e32 v14, v44, v206
	v_fmac_f32_e32 v15, v44, v207
	v_fmac_f32_e32 v8, v52, v204
	v_fmac_f32_e32 v9, v52, v205
	v_fmac_f32_e32 v10, v52, v206
	v_fmac_f32_e32 v11, v52, v207
	v_fmac_f32_e32 v4, v218, v204
	v_fmac_f32_e32 v5, v218, v205
	v_fmac_f32_e32 v6, v218, v206
	v_fmac_f32_e32 v7, v218, v207
	v_fmac_f32_e32 v0, v226, v204
	v_fmac_f32_e32 v1, v226, v205
	v_fmac_f32_e32 v2, v226, v206
	v_fmac_f32_e32 v3, v226, v207
	s_waitcnt vmcnt(0)
	v_fmac_f32_e32 v16, v35, v208
	v_fmac_f32_e32 v17, v35, v209
	v_fmac_f32_e32 v18, v35, v210
	v_fmac_f32_e32 v19, v35, v211
	v_fmac_f32_e32 v12, v45, v208
	v_fmac_f32_e32 v13, v45, v209
	v_fmac_f32_e32 v14, v45, v210
	v_fmac_f32_e32 v15, v45, v211
	v_fmac_f32_e32 v8, v53, v208
	v_fmac_f32_e32 v9, v53, v209
	v_fmac_f32_e32 v10, v53, v210
	v_fmac_f32_e32 v11, v53, v211
	v_fmac_f32_e32 v4, v219, v208
	v_fmac_f32_e32 v5, v219, v209
	v_fmac_f32_e32 v6, v219, v210
	v_fmac_f32_e32 v7, v219, v211
	v_fmac_f32_e32 v0, v227, v208
	v_fmac_f32_e32 v1, v227, v209
	v_fmac_f32_e32 v2, v227, v210
	v_fmac_f32_e32 v3, v227, v211
	s_cmp_lg_u32 s2, 0x300000
	s_cbranch_scc1 .LBB0_534
; __device__ __forceinline__ void modp_task(const Params& p, int l, int task, LAS float* sl) {
;     ...
;     float* mp = (float*)(p.ws + OFF_MODP) + ((size_t)(s * 2 + l) * 5) * 12288 + n0;
; #pragma unroll
;     for (int r = 0; r < 5; ++r) *(f32x4*)(mp + (size_t)r * 12288) = acc[r];
;     __syncthreads();
; __global__ void __launch_bounds__(512, 2) mega(Params p_unused) {
;     ...
;             if (l == 0 && bid >= 160) { __syncthreads(); for (int it = bid - 160; it < 192; it += G - 160) modp_task(p, 1, it, ldsf); }
	s_lshl_b32 s2, s18, 1
	s_or_b32 s2, s2, 1
	s_mul_hi_i32 s3, s2, 0x3c000
	s_mul_i32 s2, s2, 0x3c000
	s_add_u32 s2, s1, s2
	s_addc_u32 s3, s8, s3
	v_lshl_add_u64 v[20:21], v[20:21], 2, s[2:3]
	s_mov_b32 s2, 0xc000
	global_store_dwordx4 v[20:21], v[16:19], off
	s_nop 1
	v_add_co_u32_e32 v16, vcc, s2, v20
	s_mov_b32 s2, 0x18000
	s_nop 0
	v_addc_co_u32_e32 v17, vcc, 0, v21, vcc
	global_store_dwordx4 v[16:17], v[12:15], off
	s_nop 1
	v_add_co_u32_e32 v12, vcc, s2, v20
	v_readlane_b32 s2, v239, 43
	s_nop 0
	v_addc_co_u32_e32 v13, vcc, 0, v21, vcc
	global_store_dwordx4 v[12:13], v[8:11], off
	s_add_i32 s9, s2, s9
	s_cmpk_lt_i32 s9, 0xc0
	v_add_co_u32_e32 v8, vcc, 0x24000, v20
	s_nop 1
	v_addc_co_u32_e32 v9, vcc, 0, v21, vcc
	global_store_dwordx4 v[8:9], v[4:7], off
	s_nop 1
	v_add_co_u32_e32 v4, vcc, 0x30000, v20
	s_nop 1
	v_addc_co_u32_e32 v5, vcc, 0, v21, vcc
	global_store_dwordx4 v[4:5], v[0:3], off
	s_barrier
	s_cbranch_scc1 .LBB0_531
